# speedup vs baseline: 1.0106x; 1.0028x over previous
; __device__ __forceinline__ void rope_entries(float* tab, int item, const int wv) {
;   const int e = item * 512 + opaque_tid(wv);
;   const int pos = e >> 7, i = e & 127;
;   double r = 0.93057204092969897;
;   double inv = 1.0;
;   #pragma unroll
;   for (int b = 0; b < 7; ++b) { if ((i >> b) & 1) inv *= r; r *= r; }
;   const double ang = (double)pos * inv;
;   const double kq = rint(ang * 0.63661977236758134);
;   double rr = fma(-kq, 1.5707963267948966, ang);
;   rr = fma(-kq, 6.123233995736766e-17, rr);
;   const double r2 = rr * rr;
;   double sp = -7.6471637318198164e-13;
;   sp = fma(sp, r2, 1.6059043836821613e-10);
;   sp = fma(sp, r2, -2.5052108385441720e-08);
;   sp = fma(sp, r2, 2.7557319223985893e-06);
;   sp = fma(sp, r2, -1.9841269841269841e-04);
;   sp = fma(sp, r2, 8.3333333333333332e-03);
;   sp = fma(sp, r2, -1.6666666666666666e-01);
;   const double sn = fma(sp * r2, rr, rr);
;   double cp = 4.7794773323873853e-14;
;   cp = fma(cp, r2, -1.1470745597729725e-11);
;   cp = fma(cp, r2, 2.0876756987868100e-09);
;   cp = fma(cp, r2, -2.7557319223985888e-07);
;   cp = fma(cp, r2, 2.4801587301587302e-05);
;   cp = fma(cp, r2, -1.3888888888888889e-03);
;   cp = fma(cp, r2, 4.1666666666666664e-02);
;   cp = fma(cp, r2, -0.5);
;   const double cn = fma(cp, r2, 1.0);
; __device__ __forceinline__ void phase0(const Params& p, char* smem, const int wv) {
;   char* ws = p.ws;
;   constexpr int NA = 64 * 48, NB = 64 * 16, NC = 64 * 65, ND = 64 * 16, NE = 64, NF = 2048, NG = 1024, NH = 240;
;   constexpr int TOT = NA + NB + NC + ND + NE + NF + NG + NH;
;   #pragma unroll 1
;   for (int it = blockIdx.x; it < TOT; it += gridDim.x) {
.LBB0_3:
	s_andn2_b64 vcc, exec, s[0:1]
	v_writelane_b32 v255, s2, 9
	s_lshr_b32 s0, s2, 6
	v_writelane_b32 v255, s0, 10
	v_writelane_b32 v255, s68, 11
	s_nop 1
	v_writelane_b32 v255, s69, 12
	v_writelane_b32 v255, s70, 13
	v_writelane_b32 v255, s71, 14
	v_writelane_b32 v255, s91, 15
	s_cbranch_vccnz .LBB0_229
	s_add_u32 s3, s96, 0xe020000
	v_readlane_b32 s1, v255, 10
	s_addc_u32 s48, s97, 0
	s_lshl_b32 s49, s1, 10
	s_add_u32 s6, s96, 0x1a400000
	v_readlane_b32 s0, v255, 9
	s_addc_u32 s7, s97, 0
	s_and_b32 s67, s0, 0xffffffc0
	s_add_u32 s50, s96, 0x12400000
	s_addc_u32 s51, s97, 0
	s_add_u32 s52, s96, 0x12200000
	s_mul_i32 s0, s1, 0x404
	s_addc_u32 s53, s97, 0
	s_add_i32 s54, s0, 0
	s_add_u32 s55, s96, 0x10200000
	s_addc_u32 s56, s97, 0
	s_add_u32 s57, s96, 0x6000000
	s_addc_u32 s58, s97, 0
	s_add_u32 s59, s96, 0x8000000
	v_readlane_b32 s2, v255, 8
	s_addc_u32 s60, s97, 0
	s_lshl_b32 s0, s2, 8
	s_or_b32 s61, s0, 0xc0
	s_lshl_b32 s0, s2, 9
	s_add_i32 s63, s0, 0xffa70000
	s_lshl_b32 s0, s2, 3
	s_add_i32 s0, s1, s0
	s_mov_b32 s18, 0x6248490a
	s_mov_b32 s20, 0x9999998d
	s_mov_b32 s22, 0x47ae1467
	s_mov_b32 s24, 0x6dc9c883
	s_mov_b32 s26, 0x54442d18
	s_mov_b32 s28, 0x33145c07
	s_mov_b32 s30, 0xe733b81f
	v_mov_b32_e32 v67, 0
	s_mov_b32 s9, 0
	s_lshl_b32 s62, s91, 8
	s_lshl_b32 s64, s91, 9
	s_add_i32 s10, s0, 0xfffedc00
	s_lshl_b32 s65, s91, 3
	s_lshl_b32 s66, s2, 5
	s_lshl_b32 s16, s91, 5
	s_lshl_b32 s88, s2, 2
	s_lshl_b32 s89, s91, 2
	s_mov_b32 s19, 0x3fd43d13
	s_mov_b32 s21, 0x3fb99999
	s_mov_b32 s23, 0x3f847ae1
	s_mov_b32 s25, 0x3fe45f30
	s_mov_b32 s27, 0xbff921fb
	s_mov_b32 s29, 0xbc91a626
	s_mov_b32 s31, 0xbd6ae7f3
	s_mov_b32 s35, 0x3d2ae7f3
	s_movk_i32 s90, 0x200
	v_mov_b32_e32 v92, 0x358637bd
	v_mov_b32_e32 v93, 0x260
	s_movk_i32 s91, 0x1000
	s_movk_i32 s92, 0x4010
	s_movk_i32 s93, 0xfff
	s_movk_i32 s94, 0x17ff
	s_movk_i32 s95, 0x180f
	s_movk_i32 s12, 0x200f
	s_movk_i32 s13, 0x280f
	s_movk_i32 s14, 0x300f
	s_movk_i32 s15, 0x3000
	v_mov_b32_e32 v100, v67
	v_mov_b32_e32 v101, v67
	v_mov_b32_e32 v102, v67
	v_mov_b32_e32 v103, v67
	v_mov_b32_e32 v94, 0x3fedc73f
	v_mov_b32_e32 v95, 0x3ff00000
	v_mov_b32_e32 v68, 0x13a86d09
	v_mov_b32_e32 v69, 0x3de61246
	v_mov_b32_e32 v70, 0x67f544e4
	v_mov_b32_e32 v71, 0xbe5ae645
	v_mov_b32_e32 v72, 0xa556c734
	v_mov_b32_e32 v73, 0x3ec71de3
	v_mov_b32_e32 v74, 0x1a01a01a
	v_mov_b32_e32 v75, 0xbf2a01a0
	v_mov_b32_e32 v76, 0x11111111
	v_mov_b32_e32 v77, 0x3f811111
	v_mov_b32_e32 v78, 0x55555555
	v_mov_b32_e32 v79, 0xbfc55555
	v_mov_b32_e32 v80, 0xa8c07c9d
	v_mov_b32_e32 v81, 0xbda93974
	v_mov_b32_e32 v82, 0xeff8d898
	v_mov_b32_e32 v83, 0x3e21eed8
	v_mov_b32_e32 v84, 0xb7789f5c
	v_mov_b32_e32 v85, 0xbe927e4f
	v_mov_b32_e32 v87, 0x3efa01a0
	v_mov_b32_e32 v88, 0x16c16c17
	v_mov_b32_e32 v89, 0xbf56c16c
	v_mov_b32_e32 v91, 0x3fa55555
	v_mov_b32_e32 v96, 0x10040
	v_mov_b32_e32 v97, 0xc000
	v_mbcnt_lo_u32_b32 v230, -1, 0
	v_mbcnt_hi_u32_b32 v230, -1, v230
	s_nop 0
	v_and_b32_e32 v230, 63, v230
	v_lshlrev_b32_e32 v230, 4, v230
	v_add_u32_e32 v231, 0x1000, v230
	v_add_u32_e32 v232, 0x2000, v230
	v_add_u32_e32 v233, 0x3000, v230
	global_load_dwordx4 v[166:169], v230, s[74:75]
	global_load_dwordx4 v[170:173], v230, s[74:75] offset:1024
	global_load_dwordx4 v[174:177], v230, s[74:75] offset:2048
	global_load_dwordx4 v[178:181], v230, s[74:75] offset:3072
	global_load_dwordx4 v[182:185], v231, s[74:75]
	global_load_dwordx4 v[186:189], v231, s[74:75] offset:1024
	global_load_dwordx4 v[190:193], v231, s[74:75] offset:2048
	global_load_dwordx4 v[194:197], v231, s[74:75] offset:3072
	global_load_dwordx4 v[198:201], v232, s[74:75]
	global_load_dwordx4 v[202:205], v232, s[74:75] offset:1024
	global_load_dwordx4 v[206:209], v232, s[74:75] offset:2048
	global_load_dwordx4 v[210:213], v232, s[74:75] offset:3072
	global_load_dwordx4 v[214:217], v233, s[74:75]
	global_load_dwordx4 v[218:221], v233, s[74:75] offset:1024
	global_load_dwordx4 v[222:225], v233, s[74:75] offset:2048
	global_load_dwordx4 v[226:229], v233, s[74:75] offset:3072
	s_branch .LBB0_9

; __device__ __forceinline__ void rmsnorm_rows(const float* x, const float* g, u16* H, int item, const int wv) {
;   const int tid = opaque_tid(wv);
;   const int wid = wv, lane = tid & 63;
;   const int row = item * 8 + wid;
;   const float4* xr = (const float4*)(x + (long)row * D);
;   float4 v[16]; float ss = 0.f;
;   #pragma unroll
;   for (int i = 0; i < 16; ++i) { v[i] = xr[i * 64 + lane]; ss += v[i].x * v[i].x + v[i].y * v[i].y + v[i].z * v[i].z + v[i].w * v[i].w; }
;   #pragma unroll
;   for (int d = 32; d >= 1; d >>= 1) ss += sx(ss, d, lane);
.LBB0_30:
	s_andn2_b64 vcc, exec, s[0:1]
	s_cbranch_vccnz .LBB0_32
	s_mov_b32 s11, s9
	v_mbcnt_lo_u32_b32 v2, -1, 0
	v_mbcnt_hi_u32_b32 v2, -1, v2
	s_lshl_b64 s[0:1], s[10:11], 14
	v_and_b32_e32 v99, 63, v2
	s_add_u32 s0, s72, s0
	v_or_b32_e32 v90, 0x380, v99
	s_addc_u32 s1, s73, s1
	v_lshlrev_b32_e32 v98, 4, v90
	v_or_b32_e32 v66, 0x3c0, v99
	v_lshlrev_b32_e32 v86, 4, v66
	global_load_dwordx4 v[6:9], v98, s[0:1]
	global_load_dwordx4 v[2:5], v86, s[0:1]
	v_lshlrev_b32_e32 v144, 4, v99
	v_or_b32_e32 v147, 0x140, v99
	v_or_b32_e32 v145, 0x100, v99
	global_load_dwordx4 v[46:49], v144, s[0:1]
	global_load_dwordx4 v[38:41], v144, s[0:1] offset:1024
	global_load_dwordx4 v[34:37], v144, s[0:1] offset:2048
	v_lshlrev_b32_e32 v148, 4, v147
	v_or_b32_e32 v149, 0x180, v99
	v_lshlrev_b32_e32 v146, 4, v145
	global_load_dwordx4 v[30:33], v144, s[0:1] offset:3072
	global_load_dwordx4 v[26:29], v146, s[0:1]
	v_lshlrev_b32_e32 v150, 4, v149
	global_load_dwordx4 v[22:25], v148, s[0:1]
	global_load_dwordx4 v[18:21], v150, s[0:1]
	v_or_b32_e32 v151, 0x1c0, v99
	v_lshlrev_b32_e32 v152, 4, v151
	global_load_dwordx4 v[14:17], v152, s[0:1]
	v_or_b32_e32 v153, 0x200, v99
	v_lshlrev_b32_e32 v154, 4, v153
	global_load_dwordx4 v[10:13], v154, s[0:1]
	v_or_b32_e32 v155, 0x240, v99
	v_lshlrev_b32_e32 v156, 4, v155
	global_load_dwordx4 v[62:65], v156, s[0:1]
	v_or_b32_e32 v157, 0x280, v99
	v_lshlrev_b32_e32 v158, 4, v157
	global_load_dwordx4 v[54:57], v158, s[0:1]
	v_or_b32_e32 v159, 0x2c0, v99
	v_lshlrev_b32_e32 v160, 4, v159
	global_load_dwordx4 v[58:61], v160, s[0:1]
	v_or_b32_e32 v161, 0x300, v99
	v_lshlrev_b32_e32 v162, 4, v161
	global_load_dwordx4 v[50:53], v162, s[0:1]
	v_or_b32_e32 v163, 0x340, v99
	v_lshlrev_b32_e32 v164, 4, v163
	global_load_dwordx4 v[42:45], v164, s[0:1]
	s_mov_b32 s0, 0xf800000
	s_waitcnt vmcnt(15)
	v_mov_b32_e32 v110, v7
	s_waitcnt vmcnt(14)
	v_mov_b32_e32 v111, v3
	v_mov_b32_e32 v108, v6
	v_mov_b32_e32 v109, v2
	s_waitcnt vmcnt(13)
	v_pk_mul_f32 v[116:117], v[46:47], v[46:47]
	s_waitcnt vmcnt(12)
	v_pk_mul_f32 v[118:119], v[38:39], v[38:39]
	s_waitcnt vmcnt(11)
	v_pk_mul_f32 v[120:121], v[34:35], v[34:35]
	v_pk_mul_f32 v[110:111], v[110:111], v[110:111]
	v_mov_b32_e32 v112, v8
	v_mov_b32_e32 v113, v4
	s_waitcnt vmcnt(8)
	v_pk_mul_f32 v[126:127], v[22:23], v[22:23]
	v_pk_mul_f32 v[124:125], v[26:27], v[26:27]
	v_pk_mul_f32 v[132:133], v[40:41], v[40:41]
	v_pk_mul_f32 v[140:141], v[24:25], v[24:25]
	v_add_f32_e32 v118, v118, v119
	v_add_f32_e32 v116, v116, v117
	v_add_f32_e32 v117, v120, v121
	v_add_f32_e32 v121, v126, v127
	v_pk_fma_f32 v[108:109], v[108:109], v[108:109], v[110:111]
	v_pk_mul_f32 v[122:123], v[30:31], v[30:31]
	s_waitcnt vmcnt(7)
	v_pk_mul_f32 v[128:129], v[18:19], v[18:19]
	v_pk_mul_f32 v[130:131], v[48:49], v[48:49]
	v_pk_mul_f32 v[134:135], v[36:37], v[36:37]
	v_pk_mul_f32 v[138:139], v[28:29], v[28:29]
	v_add_f32_e32 v120, v124, v125
	v_add_f32_e32 v110, v118, v132
	v_pk_fma_f32 v[108:109], v[112:113], v[112:113], v[108:109]
	v_add_f32_e32 v112, v121, v140
	v_pk_mul_f32 v[136:137], v[32:33], v[32:33]
	v_pk_mul_f32 v[142:143], v[20:21], v[20:21]
	v_add_f32_e32 v119, v122, v123
	v_add_f32_e32 v122, v128, v129
	v_add_f32_e32 v111, v116, v130
	v_add_f32_e32 v116, v117, v134
	v_add_f32_e32 v118, v110, v133
	v_add_f32_e32 v110, v120, v138
	v_add_f32_e32 v121, v112, v141
	s_waitcnt vmcnt(6)
	v_pk_mul_f32 v[112:113], v[14:15], v[14:15]
	v_add_f32_e32 v117, v119, v136
	v_add_f32_e32 v119, v111, v131
	v_add_f32_e32 v123, v116, v135
	v_add_f32_e32 v120, v110, v139
	v_pk_mul_f32 v[110:111], v[16:17], v[16:17]
	v_add_f32_e32 v116, v122, v142
	v_add_f32_e32 v112, v112, v113
	v_add_f32_e32 v124, v117, v137
	v_add_f32_e32 v122, v116, v143
	s_waitcnt vmcnt(5)
	v_pk_mul_f32 v[116:117], v[10:11], v[10:11]
	v_add_f32_e32 v110, v112, v110
	v_add_f32_e32 v112, v110, v111
	v_add_f32_e32 v113, v116, v117
	v_pk_mul_f32 v[110:111], v[12:13], v[12:13]
	v_mov_b32_e32 v114, v9
	v_add_f32_e32 v110, v113, v110
	v_mov_b32_e32 v115, v5
	v_add_f32_e32 v113, v110, v111
	s_waitcnt vmcnt(4)
	v_pk_mul_f32 v[110:111], v[62:63], v[62:63]
	v_pk_fma_f32 v[108:109], v[114:115], v[114:115], v[108:109]
	v_add_f32_e32 v114, v110, v111
	v_pk_mul_f32 v[110:111], v[64:65], v[64:65]
	s_nop 0
	v_add_f32_e32 v110, v114, v110
	v_add_f32_e32 v114, v110, v111
	s_waitcnt vmcnt(3)
	v_pk_mul_f32 v[110:111], v[54:55], v[54:55]
	s_nop 0
	v_add_f32_e32 v115, v110, v111
	v_pk_mul_f32 v[110:111], v[56:57], v[56:57]
	s_nop 0
	v_add_f32_e32 v110, v115, v110
	v_add_f32_e32 v115, v110, v111
	s_waitcnt vmcnt(2)
	v_pk_mul_f32 v[110:111], v[58:59], v[58:59]
	s_nop 0
	v_add_f32_e32 v116, v110, v111
	v_pk_mul_f32 v[110:111], v[60:61], v[60:61]
	s_nop 0
	v_add_f32_e32 v110, v116, v110
	v_add_f32_e32 v116, v110, v111
	s_waitcnt vmcnt(1)
	v_pk_mul_f32 v[110:111], v[50:51], v[50:51]
	s_nop 0
	v_add_f32_e32 v117, v110, v111
	v_pk_mul_f32 v[110:111], v[52:53], v[52:53]
	s_nop 0
	v_add_f32_e32 v110, v117, v110
	v_add_f32_e32 v117, v110, v111
	s_waitcnt vmcnt(0)
	v_pk_mul_f32 v[110:111], v[42:43], v[42:43]
	s_nop 0
	v_add_f32_e32 v125, v110, v111
	v_pk_mul_f32 v[110:111], v[44:45], v[44:45]
	s_nop 0
	v_add_f32_e32 v110, v125, v110
	v_add_f32_e32 v110, v110, v111
	v_add_f32_e32 v111, v119, v118
	v_add_f32_e32 v111, v111, v123
	v_add_f32_e32 v111, v111, v124
	v_add_f32_e32 v111, v111, v120
	v_add_f32_e32 v111, v111, v121
	v_add_f32_e32 v111, v111, v122
	v_add_f32_e32 v111, v111, v112
	v_add_f32_e32 v111, v111, v113
	v_add_f32_e32 v111, v111, v114
	v_add_f32_e32 v111, v111, v115
	v_add_f32_e32 v111, v111, v116
	v_add_f32_e32 v111, v111, v117
	v_add_f32_e32 v110, v111, v110
	v_add_f32_e32 v108, v110, v108
	v_add_f32_e32 v108, v108, v109
	v_lshlrev_b32_e32 v109, 2, v99
	v_xor_b32_e32 v110, 0x80, v109
	ds_bpermute_b32 v110, v110, v108
	v_lshlrev_b32_e32 v99, 3, v99
	s_waitcnt lgkmcnt(0)
; __device__ __forceinline__ void rmsnorm_rows(const float* x, const float* g, u16* H, int item, const int wv) {
;     ...
;   for (int d = 32; d >= 1; d >>= 1) ss += sx(ss, d, lane);
	v_add_f32_e32 v108, v108, v110
	v_xor_b32_e32 v110, 64, v109
	ds_bpermute_b32 v110, v110, v108
	s_waitcnt lgkmcnt(0)
	v_add_f32_e32 v108, v108, v110
	v_xor_b32_e32 v110, 32, v109
	ds_bpermute_b32 v110, v110, v108
	s_waitcnt lgkmcnt(0)
	v_add_f32_e32 v108, v108, v110
	v_xor_b32_e32 v110, 16, v109
	ds_bpermute_b32 v110, v110, v108
	s_waitcnt lgkmcnt(0)
	v_add_f32_e32 v108, v108, v110
	v_xor_b32_e32 v110, 8, v109
	ds_bpermute_b32 v110, v110, v108
	v_xor_b32_e32 v109, 4, v109
	s_waitcnt lgkmcnt(0)
	v_add_f32_e32 v108, v108, v110
	ds_bpermute_b32 v109, v109, v108
	s_waitcnt lgkmcnt(0)
; __device__ __forceinline__ void rmsnorm_rows(const float* x, const float* g, u16* H, int item, const int wv) {
;     ...
;   const float rstd = 1.0f / sqrtf(ss * (1.0f / D) + EPS);
;   #pragma unroll
;   for (int i = 0; i < 16; ++i) {
;     float4 g4 = ((const float4*)g)[i * 64 + lane];
;     uint2 pk; pk.x = pack2(v[i].x * rstd * g4.x, v[i].y * rstd * g4.y); pk.y = pack2(v[i].z * rstd * g4.z, v[i].w * rstd * g4.w);
;     *(uint2*)(H + (long)row * D + (i * 64 + lane) * 4) = pk;
;   }
	v_add_f32_e32 v108, v108, v109
	v_fmamk_f32 v108, v108, 0x39800000, v92
	v_mul_f32_e32 v109, 0x4f800000, v108
	v_cmp_gt_f32_e32 vcc, s0, v108
	s_nop 1
	v_cndmask_b32_e32 v108, v108, v109, vcc
	v_sqrt_f32_e32 v109, v108
	s_nop 0
	v_add_u32_e32 v110, -1, v109
	v_fma_f32 v111, -v110, v109, v108
	v_cmp_ge_f32_e64 s[0:1], 0, v111
	v_add_u32_e32 v111, 1, v109
	s_nop 0
	v_cndmask_b32_e64 v110, v109, v110, s[0:1]
	v_fma_f32 v109, -v111, v109, v108
	v_cmp_lt_f32_e64 s[0:1], 0, v109
	s_nop 1
	v_cndmask_b32_e64 v109, v110, v111, s[0:1]
	v_mul_f32_e32 v110, 0x37800000, v109
	v_cndmask_b32_e32 v109, v109, v110, vcc
	v_cmp_class_f32_e32 vcc, v108, v93
	s_nop 1
	v_cndmask_b32_e32 v108, v109, v108, vcc
	v_div_scale_f32 v109, s[0:1], v108, v108, 1.0
	v_rcp_f32_e32 v110, v109
	s_lshl_b64 s[0:1], s[10:11], 13
	s_add_u32 s0, s50, s0
	s_addc_u32 s1, s51, s1
	v_fma_f32 v111, -v109, v110, 1.0
	v_fmac_f32_e32 v110, v111, v110
	v_div_scale_f32 v111, vcc, 1.0, v108, 1.0
	v_mul_f32_e32 v112, v111, v110
	v_fma_f32 v113, -v109, v112, v111
	v_fmac_f32_e32 v112, v113, v110
	v_fma_f32 v109, -v109, v112, v111
	v_div_fmas_f32 v109, v109, v110, v112
	v_div_fixup_f32 v108, v109, v108, 1.0
	v_pk_mul_f32 v[46:47], v[46:47], v[108:109] op_sel_hi:[1,0]
	v_pk_mul_f32 v[48:49], v[48:49], v[108:109] op_sel_hi:[1,0]
	v_pk_mul_f32 v[46:47], v[166:167], v[46:47]
	v_pk_mul_f32 v[48:49], v[168:169], v[48:49]
	v_cvt_pk_bf16_f32 v46, v46, v47
	v_cvt_pk_bf16_f32 v47, v48, v49
	global_store_dwordx2 v99, v[46:47], s[0:1]
	v_pk_mul_f32 v[38:39], v[38:39], v[108:109] op_sel_hi:[1,0]
	v_pk_mul_f32 v[40:41], v[40:41], v[108:109] op_sel_hi:[1,0]
	v_or_b32_e32 v104, 0x200, v99
	v_pk_mul_f32 v[34:35], v[34:35], v[108:109] op_sel_hi:[1,0]
	v_pk_mul_f32 v[36:37], v[36:37], v[108:109] op_sel_hi:[1,0]
	v_pk_mul_f32 v[30:31], v[30:31], v[108:109] op_sel_hi:[1,0]
	v_pk_mul_f32 v[32:33], v[32:33], v[108:109] op_sel_hi:[1,0]
	v_pk_mul_f32 v[26:27], v[26:27], v[108:109] op_sel_hi:[1,0]
	v_pk_mul_f32 v[28:29], v[28:29], v[108:109] op_sel_hi:[1,0]
	v_pk_mul_f32 v[22:23], v[22:23], v[108:109] op_sel_hi:[1,0]
	v_pk_mul_f32 v[24:25], v[24:25], v[108:109] op_sel_hi:[1,0]
	v_pk_mul_f32 v[18:19], v[18:19], v[108:109] op_sel_hi:[1,0]
	v_pk_mul_f32 v[20:21], v[20:21], v[108:109] op_sel_hi:[1,0]
	v_pk_mul_f32 v[14:15], v[14:15], v[108:109] op_sel_hi:[1,0]
	v_pk_mul_f32 v[16:17], v[16:17], v[108:109] op_sel_hi:[1,0]
	v_pk_mul_f32 v[10:11], v[10:11], v[108:109] op_sel_hi:[1,0]
	v_pk_mul_f32 v[12:13], v[12:13], v[108:109] op_sel_hi:[1,0]
	v_pk_mul_f32 v[6:7], v[6:7], v[108:109] op_sel_hi:[1,0]
	v_pk_mul_f32 v[8:9], v[8:9], v[108:109] op_sel_hi:[1,0]
	v_pk_mul_f32 v[2:3], v[2:3], v[108:109] op_sel_hi:[1,0]
	v_pk_mul_f32 v[4:5], v[4:5], v[108:109] op_sel_hi:[1,0]
	v_pk_mul_f32 v[38:39], v[170:171], v[38:39]
	v_pk_mul_f32 v[40:41], v[40:41], v[172:173]
	v_cvt_pk_bf16_f32 v38, v38, v39
	v_cvt_pk_bf16_f32 v39, v40, v41
	global_store_dwordx2 v104, v[38:39], s[0:1]
	v_or_b32_e32 v46, 0x400, v99
	v_pk_mul_f32 v[34:35], v[34:35], v[174:175]
	v_pk_mul_f32 v[36:37], v[36:37], v[176:177]
	v_cvt_pk_bf16_f32 v34, v34, v35
	v_cvt_pk_bf16_f32 v35, v36, v37
	global_store_dwordx2 v46, v[34:35], s[0:1]
	v_or_b32_e32 v38, 0x600, v99
	v_pk_mul_f32 v[30:31], v[30:31], v[178:179]
	v_pk_mul_f32 v[32:33], v[32:33], v[180:181]
	v_cvt_pk_bf16_f32 v30, v30, v31
	v_cvt_pk_bf16_f32 v31, v32, v33
	global_store_dwordx2 v38, v[30:31], s[0:1]
	v_lshlrev_b32_e32 v34, 3, v145
	v_pk_mul_f32 v[26:27], v[26:27], v[182:183]
	v_pk_mul_f32 v[28:29], v[28:29], v[184:185]
	v_cvt_pk_bf16_f32 v26, v26, v27
	v_cvt_pk_bf16_f32 v27, v28, v29
	global_store_dwordx2 v34, v[26:27], s[0:1]
	v_lshlrev_b32_e32 v30, 3, v147
	v_pk_mul_f32 v[22:23], v[22:23], v[186:187]
	v_pk_mul_f32 v[24:25], v[24:25], v[188:189]
	v_cvt_pk_bf16_f32 v22, v22, v23
	v_cvt_pk_bf16_f32 v23, v24, v25
	global_store_dwordx2 v30, v[22:23], s[0:1]
	v_lshlrev_b32_e32 v26, 3, v149
	v_pk_mul_f32 v[18:19], v[18:19], v[190:191]
	v_pk_mul_f32 v[20:21], v[20:21], v[192:193]
	v_cvt_pk_bf16_f32 v18, v18, v19
	v_cvt_pk_bf16_f32 v19, v20, v21
	global_store_dwordx2 v26, v[18:19], s[0:1]
	v_lshlrev_b32_e32 v22, 3, v151
	v_pk_mul_f32 v[14:15], v[14:15], v[194:195]
	v_pk_mul_f32 v[16:17], v[16:17], v[196:197]
	v_cvt_pk_bf16_f32 v14, v14, v15
	v_cvt_pk_bf16_f32 v15, v16, v17
	global_store_dwordx2 v22, v[14:15], s[0:1]
	v_lshlrev_b32_e32 v18, 3, v153
	v_pk_mul_f32 v[10:11], v[10:11], v[198:199]
	v_pk_mul_f32 v[12:13], v[12:13], v[200:201]
	v_cvt_pk_bf16_f32 v10, v10, v11
	v_cvt_pk_bf16_f32 v11, v12, v13
	global_store_dwordx2 v18, v[10:11], s[0:1]
	v_pk_mul_f32 v[14:15], v[62:63], v[108:109] op_sel_hi:[1,0]
	v_pk_mul_f32 v[16:17], v[64:65], v[108:109] op_sel_hi:[1,0]
	v_lshlrev_b32_e32 v18, 3, v155
	v_pk_mul_f32 v[10:11], v[14:15], v[202:203]
	v_pk_mul_f32 v[12:13], v[16:17], v[204:205]
	v_cvt_pk_bf16_f32 v10, v10, v11
	v_cvt_pk_bf16_f32 v11, v12, v13
	global_store_dwordx2 v18, v[10:11], s[0:1]
	v_pk_mul_f32 v[14:15], v[54:55], v[108:109] op_sel_hi:[1,0]
	v_pk_mul_f32 v[16:17], v[56:57], v[108:109] op_sel_hi:[1,0]
	v_lshlrev_b32_e32 v18, 3, v157
	v_pk_mul_f32 v[10:11], v[14:15], v[206:207]
	v_pk_mul_f32 v[12:13], v[16:17], v[208:209]
	v_cvt_pk_bf16_f32 v10, v10, v11
	v_cvt_pk_bf16_f32 v11, v12, v13
	global_store_dwordx2 v18, v[10:11], s[0:1]
	v_pk_mul_f32 v[14:15], v[58:59], v[108:109] op_sel_hi:[1,0]
	v_pk_mul_f32 v[16:17], v[60:61], v[108:109] op_sel_hi:[1,0]
	v_lshlrev_b32_e32 v18, 3, v159
	v_pk_mul_f32 v[10:11], v[14:15], v[210:211]
	v_pk_mul_f32 v[12:13], v[16:17], v[212:213]
	v_cvt_pk_bf16_f32 v10, v10, v11
	v_cvt_pk_bf16_f32 v11, v12, v13
	global_store_dwordx2 v18, v[10:11], s[0:1]
	v_pk_mul_f32 v[14:15], v[50:51], v[108:109] op_sel_hi:[1,0]
	v_pk_mul_f32 v[16:17], v[52:53], v[108:109] op_sel_hi:[1,0]
	v_lshlrev_b32_e32 v18, 3, v161
	v_pk_mul_f32 v[10:11], v[14:15], v[214:215]
	v_pk_mul_f32 v[12:13], v[16:17], v[216:217]
	v_cvt_pk_bf16_f32 v10, v10, v11
	v_cvt_pk_bf16_f32 v11, v12, v13
	global_store_dwordx2 v18, v[10:11], s[0:1]
	v_pk_mul_f32 v[14:15], v[42:43], v[108:109] op_sel_hi:[1,0]
	v_pk_mul_f32 v[16:17], v[44:45], v[108:109] op_sel_hi:[1,0]
	v_lshlrev_b32_e32 v18, 3, v163
	v_pk_mul_f32 v[10:11], v[14:15], v[218:219]
	v_pk_mul_f32 v[12:13], v[16:17], v[220:221]
	v_cvt_pk_bf16_f32 v10, v10, v11
	v_cvt_pk_bf16_f32 v11, v12, v13
	global_store_dwordx2 v18, v[10:11], s[0:1]
	v_lshlrev_b32_e32 v14, 3, v90
	v_pk_mul_f32 v[6:7], v[6:7], v[222:223]
	v_pk_mul_f32 v[8:9], v[8:9], v[224:225]
	v_cvt_pk_bf16_f32 v6, v6, v7
	v_cvt_pk_bf16_f32 v7, v8, v9
	global_store_dwordx2 v14, v[6:7], s[0:1]
	v_pk_mul_f32 v[2:3], v[2:3], v[226:227]
	v_pk_mul_f32 v[4:5], v[4:5], v[228:229]
	v_cvt_pk_bf16_f32 v2, v2, v3
	v_cvt_pk_bf16_f32 v3, v4, v5
	v_lshlrev_b32_e32 v4, 3, v66
	global_store_dwordx2 v4, v[2:3], s[0:1]
